# v34 + L1 epilogue rope columns: previous step's store issued after the step's four table loads (copies in spare registers), loads waited with vmcnt(1)
# baseline (speedup 1.0000x reference)
; __device__ __forceinline__ unsigned pk2(float lo, float hi) { f32x2 v = {lo, hi}; bf16x2_t b = __builtin_convertvector(v, bf16x2_t); return __builtin_bit_cast(unsigned, b); }
;     __device__ __forceinline__ void operator()(const f32x4 (&acc)[2][2][4][2], const Unit& u, int wr, int wc, int fr, int fq) const {
;     ...
;                 for (int m = 0; m < 4; ++m) {
;                     const int row = u.pm * BM + ai * HALF + wr * 64 + m * 16 + fr;
;                     f32x4 v0 = acc[ai][bj][m][0], v1 = acc[ai][bj][m][1];
;                     if (rope) {
;                         const int s = row & (SEQ - 1), ib = 8 * (fq & 1);
;                         const f32x4 c0 = *(const f32x4*)(cosT + s * 16 + ib), c1 = *(const f32x4*)(cosT + s * 16 + ib + 4);
;                         const f32x4 s0 = *(const f32x4*)(sinT + s * 16 + ib), s1 = *(const f32x4*)(sinT + s * 16 + ib + 4);
;                         f32x4 p0, p1;
; #pragma unroll
;                         for (int e = 0; e < 4; ++e) { p0[e] = __shfl_xor(v0[e], 32); p1[e] = __shfl_xor(v1[e], 32); }
;                         if (fq < 2) { v0 = v0 * c0 - p0 * s0; v1 = v1 * c1 - p1 * s1; }
;                         else        { v0 = p0 * s0 + v0 * c0; v1 = p1 * s1 + v1 * c1; }
;                     }
;                     u32x4 w; w.x = pk2(v0[0], v0[1]); w.y = pk2(v0[2], v0[3]); w.z = pk2(v1[0], v1[1]); w.w = pk2(v1[2], v1[3]);
;                     *(u32x4*)(O + (size_t)row * ldc + cg0 + 8 * fq) = w;
.LBB0_228:
	v_cvt_pk_bf16_f32 v62, v62, v63
	v_cvt_pk_bf16_f32 v63, v64, v65
	v_cvt_pk_bf16_f32 v64, v58, v59
	v_mov_b64_e32 v[58:59], s[72:73]
	v_mad_i64_i32 v[58:59], s[4:5], v157, s19, v[58:59]
	s_ashr_i32 s27, s26, 31
	v_cvt_pk_bf16_f32 v65, v60, v61
	v_lshl_add_u64 v[58:59], s[26:27], 1, v[58:59]
	v_cndmask_b32_e64 v60, 0, 1, s[30:31]
	v_lshl_add_u64 v[58:59], v[58:59], 0, v[12:13]
	v_cmp_ne_u32_e64 s[4:5], 1, v60
	s_andn2_b64 vcc, exec, s[30:31]
	s_cbranch_vccnz .Lrope_ns_0
	v_mov_b64_e32 v[94:95], v[58:59]
	v_mov_b64_e32 v[96:97], v[62:63]
	v_mov_b64_e32 v[98:99], v[64:65]
	v_lshlrev_b32_e32 v58, 6, v156
	v_and_b32_e32 v58, 0x3f7c0, v58
	v_mov_b32_e32 v59, v13
	v_lshl_add_u64 v[66:67], v[140:141], 0, v[58:59]
	v_lshl_add_u64 v[58:59], v[142:143], 0, v[58:59]
	global_load_dwordx4 v[62:65], v[58:59], off offset:16
	global_load_dwordx4 v[74:77], v[58:59], off
	s_nop 0
	global_load_dwordx4 v[58:61], v[66:67], off offset:16
	global_load_dwordx4 v[70:73], v[66:67], off
	global_store_dwordx4 v[94:95], v[96:99], off offset:256
	v_and_b32_e32 v67, 64, v238
	v_xor_b32_e32 v66, 32, v238
	v_add_u32_e32 v67, 64, v67
	v_cmp_lt_i32_e32 vcc, v66, v67
	s_nop 1
	v_cndmask_b32_e32 v66, v238, v66, vcc
	v_lshlrev_b32_e32 v78, 2, v66
	ds_bpermute_b32 v66, v78, v54
	ds_bpermute_b32 v68, v78, v50
	ds_bpermute_b32 v67, v78, v55
	ds_bpermute_b32 v69, v78, v51
	ds_bpermute_b32 v84, v78, v56
	ds_bpermute_b32 v82, v78, v52
	ds_bpermute_b32 v85, v78, v57
	ds_bpermute_b32 v83, v78, v53
	s_waitcnt vmcnt(1) lgkmcnt(0)
	v_pk_mul_f32 v[62:63], v[62:63], v[68:69]
	v_pk_mul_f32 v[74:75], v[74:75], v[66:67]
	s_and_saveexec_b64 s[30:31], s[0:1]
	s_xor_b64 s[30:31], exec, s[30:31]
	v_pk_mul_f32 v[66:67], v[76:77], v[84:85]
	v_pk_mul_f32 v[64:65], v[64:65], v[82:83]
	v_pk_fma_f32 v[68:69], v[56:57], v[72:73], v[66:67]
	v_pk_fma_f32 v[66:67], v[54:55], v[70:71], v[74:75]
	v_pk_fma_f32 v[80:81], v[52:53], v[60:61], v[64:65]
	v_pk_fma_f32 v[78:79], v[50:51], v[58:59], v[62:63]
	s_andn2_saveexec_b64 s[30:31], s[30:31]
	v_pk_mul_f32 v[66:67], v[76:77], v[84:85]
	v_pk_fma_f32 v[78:79], v[50:51], v[58:59], v[62:63] neg_lo:[0,0,1] neg_hi:[0,0,1]
	v_pk_fma_f32 v[68:69], v[56:57], v[72:73], v[66:67] neg_lo:[0,0,1] neg_hi:[0,0,1]
	v_pk_fma_f32 v[66:67], v[54:55], v[70:71], v[74:75] neg_lo:[0,0,1] neg_hi:[0,0,1]
	v_pk_mul_f32 v[54:55], v[64:65], v[82:83]
	s_nop 0
	v_pk_fma_f32 v[80:81], v[52:53], v[60:61], v[54:55] neg_lo:[0,0,1] neg_hi:[0,0,1]
	s_or_b64 exec, exec, s[30:31]
	v_mov_b64_e32 v[50:51], v[78:79]
	v_mov_b64_e32 v[54:55], v[66:67]
	v_mov_b64_e32 v[52:53], v[80:81]
	v_mov_b64_e32 v[56:57], v[68:69]
	s_branch .LBB0_234
.Lrope_ns_0:
	global_store_dwordx4 v[58:59], v[62:65], off offset:256
	s_nop 1
.LBB0_234:
	v_cvt_pk_bf16_f32 v54, v54, v55
	v_cvt_pk_bf16_f32 v55, v56, v57
	v_cvt_pk_bf16_f32 v56, v50, v51
	v_mov_b64_e32 v[50:51], s[72:73]
	v_mad_i64_i32 v[50:51], s[30:31], v156, s19, v[50:51]
	v_lshl_add_u64 v[50:51], s[26:27], 1, v[50:51]
	v_cvt_pk_bf16_f32 v57, v52, v53
	v_lshl_add_u64 v[50:51], v[50:51], 0, v[12:13]
	s_and_b64 vcc, exec, s[4:5]
	s_cbranch_vccnz .Lrope_ns_1
	v_mov_b64_e32 v[94:95], v[50:51]
	v_mov_b64_e32 v[96:97], v[54:55]
	v_mov_b64_e32 v[98:99], v[56:57]
	v_lshlrev_b32_e32 v50, 6, v155
	v_and_b32_e32 v50, 0x3fbc0, v50
	v_mov_b32_e32 v51, v13
	v_lshl_add_u64 v[58:59], v[140:141], 0, v[50:51]
	v_lshl_add_u64 v[50:51], v[142:143], 0, v[50:51]
	global_load_dwordx4 v[54:57], v[50:51], off offset:16
	global_load_dwordx4 v[66:69], v[50:51], off
	s_nop 0
	global_load_dwordx4 v[50:53], v[58:59], off offset:16
	global_load_dwordx4 v[62:65], v[58:59], off
	global_store_dwordx4 v[94:95], v[96:99], off offset:256
	v_and_b32_e32 v59, 64, v238
	v_xor_b32_e32 v58, 32, v238
	v_add_u32_e32 v59, 64, v59
	v_cmp_lt_i32_e32 vcc, v58, v59
	s_nop 1
	v_cndmask_b32_e32 v58, v238, v58, vcc
	v_lshlrev_b32_e32 v70, 2, v58
	ds_bpermute_b32 v58, v70, v46
	ds_bpermute_b32 v60, v70, v42
	ds_bpermute_b32 v59, v70, v47
	ds_bpermute_b32 v61, v70, v43
	ds_bpermute_b32 v76, v70, v48
	ds_bpermute_b32 v74, v70, v44
	ds_bpermute_b32 v77, v70, v49
	ds_bpermute_b32 v75, v70, v45
	s_waitcnt vmcnt(1) lgkmcnt(0)
	v_pk_mul_f32 v[54:55], v[54:55], v[60:61]
	v_pk_mul_f32 v[66:67], v[66:67], v[58:59]
	s_and_saveexec_b64 s[30:31], s[0:1]
	s_xor_b64 s[30:31], exec, s[30:31]
	v_pk_mul_f32 v[58:59], v[68:69], v[76:77]
	v_pk_mul_f32 v[56:57], v[56:57], v[74:75]
	v_pk_fma_f32 v[60:61], v[48:49], v[64:65], v[58:59]
	v_pk_fma_f32 v[58:59], v[46:47], v[62:63], v[66:67]
	v_pk_fma_f32 v[72:73], v[44:45], v[52:53], v[56:57]
	v_pk_fma_f32 v[70:71], v[42:43], v[50:51], v[54:55]
	s_andn2_saveexec_b64 s[30:31], s[30:31]
	v_pk_mul_f32 v[58:59], v[68:69], v[76:77]
	v_pk_fma_f32 v[70:71], v[42:43], v[50:51], v[54:55] neg_lo:[0,0,1] neg_hi:[0,0,1]
	v_pk_fma_f32 v[60:61], v[48:49], v[64:65], v[58:59] neg_lo:[0,0,1] neg_hi:[0,0,1]
	v_pk_fma_f32 v[58:59], v[46:47], v[62:63], v[66:67] neg_lo:[0,0,1] neg_hi:[0,0,1]
	v_pk_mul_f32 v[46:47], v[56:57], v[74:75]
	s_nop 0
	v_pk_fma_f32 v[72:73], v[44:45], v[52:53], v[46:47] neg_lo:[0,0,1] neg_hi:[0,0,1]
	s_or_b64 exec, exec, s[30:31]
	v_mov_b64_e32 v[42:43], v[70:71]
	v_mov_b64_e32 v[46:47], v[58:59]
	v_mov_b64_e32 v[44:45], v[72:73]
	v_mov_b64_e32 v[48:49], v[60:61]
	s_branch .LBB0_240
.Lrope_ns_1:
	global_store_dwordx4 v[50:51], v[54:57], off offset:256
	s_nop 1
; __device__ __forceinline__ unsigned pk2(float lo, float hi) { f32x2 v = {lo, hi}; bf16x2_t b = __builtin_convertvector(v, bf16x2_t); return __builtin_bit_cast(unsigned, b); }
;     __device__ __forceinline__ void operator()(const f32x4 (&acc)[2][2][4][2], const Unit& u, int wr, int wc, int fr, int fq) const {
;     ...
;                 for (int m = 0; m < 4; ++m) {
;                     const int row = u.pm * BM + ai * HALF + wr * 64 + m * 16 + fr;
;                     f32x4 v0 = acc[ai][bj][m][0], v1 = acc[ai][bj][m][1];
;                     if (rope) {
;                         const int s = row & (SEQ - 1), ib = 8 * (fq & 1);
;                         const f32x4 c0 = *(const f32x4*)(cosT + s * 16 + ib), c1 = *(const f32x4*)(cosT + s * 16 + ib + 4);
;                         const f32x4 s0 = *(const f32x4*)(sinT + s * 16 + ib), s1 = *(const f32x4*)(sinT + s * 16 + ib + 4);
;                         f32x4 p0, p1;
; #pragma unroll
;                         for (int e = 0; e < 4; ++e) { p0[e] = __shfl_xor(v0[e], 32); p1[e] = __shfl_xor(v1[e], 32); }
;                         if (fq < 2) { v0 = v0 * c0 - p0 * s0; v1 = v1 * c1 - p1 * s1; }
;                         else        { v0 = p0 * s0 + v0 * c0; v1 = p1 * s1 + v1 * c1; }
;                     }
;                     u32x4 w; w.x = pk2(v0[0], v0[1]); w.y = pk2(v0[2], v0[3]); w.z = pk2(v1[0], v1[1]); w.w = pk2(v1[2], v1[3]);
;                     *(u32x4*)(O + (size_t)row * ldc + cg0 + 8 * fq) = w;
.LBB0_240:
	v_cvt_pk_bf16_f32 v46, v46, v47
	v_cvt_pk_bf16_f32 v47, v48, v49
	v_cvt_pk_bf16_f32 v48, v42, v43
	v_mov_b64_e32 v[42:43], s[72:73]
	v_mad_i64_i32 v[42:43], s[30:31], v155, s19, v[42:43]
	v_lshl_add_u64 v[42:43], s[26:27], 1, v[42:43]
	v_cvt_pk_bf16_f32 v49, v44, v45
	v_lshl_add_u64 v[42:43], v[42:43], 0, v[12:13]
	s_and_b64 vcc, exec, s[4:5]
	s_cbranch_vccnz .Lrope_ns_2
	v_mov_b64_e32 v[94:95], v[42:43]
	v_mov_b64_e32 v[96:97], v[46:47]
	v_mov_b64_e32 v[98:99], v[48:49]
	v_lshlrev_b32_e32 v42, 6, v154
	v_and_b32_e32 v42, 0x3ffc0, v42
	v_mov_b32_e32 v43, v13
	v_lshl_add_u64 v[50:51], v[140:141], 0, v[42:43]
	v_lshl_add_u64 v[42:43], v[142:143], 0, v[42:43]
	global_load_dwordx4 v[46:49], v[42:43], off offset:16
	global_load_dwordx4 v[58:61], v[42:43], off
	s_nop 0
	global_load_dwordx4 v[42:45], v[50:51], off offset:16
	global_load_dwordx4 v[54:57], v[50:51], off
	global_store_dwordx4 v[94:95], v[96:99], off offset:256
	v_and_b32_e32 v51, 64, v238
	v_xor_b32_e32 v50, 32, v238
	v_add_u32_e32 v51, 64, v51
	v_cmp_lt_i32_e32 vcc, v50, v51
	s_nop 1
	v_cndmask_b32_e32 v50, v238, v50, vcc
	v_lshlrev_b32_e32 v62, 2, v50
	ds_bpermute_b32 v50, v62, v38
	ds_bpermute_b32 v52, v62, v34
	ds_bpermute_b32 v51, v62, v39
	ds_bpermute_b32 v53, v62, v35
	ds_bpermute_b32 v68, v62, v40
	ds_bpermute_b32 v66, v62, v36
	ds_bpermute_b32 v69, v62, v41
	ds_bpermute_b32 v67, v62, v37
	s_waitcnt vmcnt(1) lgkmcnt(0)
	v_pk_mul_f32 v[46:47], v[46:47], v[52:53]
	v_pk_mul_f32 v[58:59], v[58:59], v[50:51]
	s_and_saveexec_b64 s[30:31], s[0:1]
	s_xor_b64 s[30:31], exec, s[30:31]
	v_pk_mul_f32 v[50:51], v[60:61], v[68:69]
	v_pk_mul_f32 v[48:49], v[48:49], v[66:67]
	v_pk_fma_f32 v[52:53], v[40:41], v[56:57], v[50:51]
	v_pk_fma_f32 v[50:51], v[38:39], v[54:55], v[58:59]
	v_pk_fma_f32 v[64:65], v[36:37], v[44:45], v[48:49]
	v_pk_fma_f32 v[62:63], v[34:35], v[42:43], v[46:47]
	s_andn2_saveexec_b64 s[30:31], s[30:31]
	v_pk_mul_f32 v[50:51], v[60:61], v[68:69]
	v_pk_fma_f32 v[62:63], v[34:35], v[42:43], v[46:47] neg_lo:[0,0,1] neg_hi:[0,0,1]
	v_pk_fma_f32 v[52:53], v[40:41], v[56:57], v[50:51] neg_lo:[0,0,1] neg_hi:[0,0,1]
	v_pk_fma_f32 v[50:51], v[38:39], v[54:55], v[58:59] neg_lo:[0,0,1] neg_hi:[0,0,1]
	v_pk_mul_f32 v[38:39], v[48:49], v[66:67]
	s_nop 0
	v_pk_fma_f32 v[64:65], v[36:37], v[44:45], v[38:39] neg_lo:[0,0,1] neg_hi:[0,0,1]
	s_or_b64 exec, exec, s[30:31]
	v_mov_b64_e32 v[34:35], v[62:63]
	v_mov_b64_e32 v[38:39], v[50:51]
	v_mov_b64_e32 v[36:37], v[64:65]
	v_mov_b64_e32 v[40:41], v[52:53]
	s_branch .LBB0_246
.Lrope_ns_2:
	global_store_dwordx4 v[42:43], v[46:49], off offset:256
	s_nop 1
.LBB0_246:
	v_cvt_pk_bf16_f32 v38, v38, v39
	v_cvt_pk_bf16_f32 v39, v40, v41
	v_cvt_pk_bf16_f32 v40, v34, v35
	v_mov_b64_e32 v[34:35], s[72:73]
	v_mad_i64_i32 v[34:35], s[30:31], v154, s19, v[34:35]
	v_lshl_add_u64 v[34:35], s[26:27], 1, v[34:35]
	v_cvt_pk_bf16_f32 v41, v36, v37
	v_lshl_add_u64 v[34:35], v[34:35], 0, v[12:13]
	s_and_b64 vcc, exec, s[4:5]
	s_cbranch_vccnz .Lrope_ns_3
	v_mov_b64_e32 v[94:95], v[34:35]
	v_mov_b64_e32 v[96:97], v[38:39]
	v_mov_b64_e32 v[98:99], v[40:41]
	v_lshlrev_b32_e32 v34, 6, v153
	v_and_b32_e32 v34, 0x3f3c0, v34
	v_mov_b32_e32 v35, v13
	v_lshl_add_u64 v[42:43], v[140:141], 0, v[34:35]
	v_lshl_add_u64 v[34:35], v[142:143], 0, v[34:35]
	global_load_dwordx4 v[38:41], v[34:35], off offset:16
	global_load_dwordx4 v[50:53], v[34:35], off
	s_nop 0
	global_load_dwordx4 v[34:37], v[42:43], off offset:16
	global_load_dwordx4 v[46:49], v[42:43], off
	global_store_dwordx4 v[94:95], v[96:99], off offset:256
	v_and_b32_e32 v43, 64, v238
	v_xor_b32_e32 v42, 32, v238
	v_add_u32_e32 v43, 64, v43
	v_cmp_lt_i32_e32 vcc, v42, v43
	s_nop 1
	v_cndmask_b32_e32 v42, v238, v42, vcc
	v_lshlrev_b32_e32 v54, 2, v42
	ds_bpermute_b32 v42, v54, v30
	ds_bpermute_b32 v44, v54, v26
	ds_bpermute_b32 v43, v54, v31
	ds_bpermute_b32 v45, v54, v27
	ds_bpermute_b32 v60, v54, v32
	ds_bpermute_b32 v58, v54, v28
	ds_bpermute_b32 v61, v54, v33
	ds_bpermute_b32 v59, v54, v29
	s_waitcnt vmcnt(1) lgkmcnt(0)
	v_pk_mul_f32 v[38:39], v[38:39], v[44:45]
	v_pk_mul_f32 v[50:51], v[50:51], v[42:43]
	s_and_saveexec_b64 s[30:31], s[0:1]
	s_xor_b64 s[30:31], exec, s[30:31]
	v_pk_mul_f32 v[42:43], v[52:53], v[60:61]
	v_pk_mul_f32 v[40:41], v[40:41], v[58:59]
	v_pk_fma_f32 v[44:45], v[32:33], v[48:49], v[42:43]
	v_pk_fma_f32 v[42:43], v[30:31], v[46:47], v[50:51]
	v_pk_fma_f32 v[56:57], v[28:29], v[36:37], v[40:41]
	v_pk_fma_f32 v[54:55], v[26:27], v[34:35], v[38:39]
	s_andn2_saveexec_b64 s[30:31], s[30:31]
	v_pk_mul_f32 v[42:43], v[52:53], v[60:61]
	v_pk_fma_f32 v[54:55], v[26:27], v[34:35], v[38:39] neg_lo:[0,0,1] neg_hi:[0,0,1]
	v_pk_fma_f32 v[44:45], v[32:33], v[48:49], v[42:43] neg_lo:[0,0,1] neg_hi:[0,0,1]
	v_pk_fma_f32 v[42:43], v[30:31], v[46:47], v[50:51] neg_lo:[0,0,1] neg_hi:[0,0,1]
	v_pk_mul_f32 v[30:31], v[40:41], v[58:59]
	s_nop 0
	v_pk_fma_f32 v[56:57], v[28:29], v[36:37], v[30:31] neg_lo:[0,0,1] neg_hi:[0,0,1]
	s_or_b64 exec, exec, s[30:31]
	v_mov_b64_e32 v[26:27], v[54:55]
	v_mov_b64_e32 v[30:31], v[42:43]
	v_mov_b64_e32 v[28:29], v[56:57]
	v_mov_b64_e32 v[32:33], v[44:45]
	s_branch .LBB0_252
.Lrope_ns_3:
	global_store_dwordx4 v[34:35], v[38:41], off offset:256
	s_nop 1
; __device__ __forceinline__ unsigned pk2(float lo, float hi) { f32x2 v = {lo, hi}; bf16x2_t b = __builtin_convertvector(v, bf16x2_t); return __builtin_bit_cast(unsigned, b); }
;     __device__ __forceinline__ void operator()(const f32x4 (&acc)[2][2][4][2], const Unit& u, int wr, int wc, int fr, int fq) const {
;     ...
;                 for (int m = 0; m < 4; ++m) {
;                     const int row = u.pm * BM + ai * HALF + wr * 64 + m * 16 + fr;
;                     f32x4 v0 = acc[ai][bj][m][0], v1 = acc[ai][bj][m][1];
;                     if (rope) {
;                         const int s = row & (SEQ - 1), ib = 8 * (fq & 1);
;                         const f32x4 c0 = *(const f32x4*)(cosT + s * 16 + ib), c1 = *(const f32x4*)(cosT + s * 16 + ib + 4);
;                         const f32x4 s0 = *(const f32x4*)(sinT + s * 16 + ib), s1 = *(const f32x4*)(sinT + s * 16 + ib + 4);
;                         f32x4 p0, p1;
; #pragma unroll
;                         for (int e = 0; e < 4; ++e) { p0[e] = __shfl_xor(v0[e], 32); p1[e] = __shfl_xor(v1[e], 32); }
;                         if (fq < 2) { v0 = v0 * c0 - p0 * s0; v1 = v1 * c1 - p1 * s1; }
;                         else        { v0 = p0 * s0 + v0 * c0; v1 = p1 * s1 + v1 * c1; }
;                     }
;                     u32x4 w; w.x = pk2(v0[0], v0[1]); w.y = pk2(v0[2], v0[3]); w.z = pk2(v1[0], v1[1]); w.w = pk2(v1[2], v1[3]);
;                     *(u32x4*)(O + (size_t)row * ldc + cg0 + 8 * fq) = w;
.LBB0_252:
	v_cvt_pk_bf16_f32 v30, v30, v31
	v_cvt_pk_bf16_f32 v31, v32, v33
	v_cvt_pk_bf16_f32 v32, v26, v27
	v_mov_b64_e32 v[26:27], s[72:73]
	v_mad_i64_i32 v[26:27], s[30:31], v153, s19, v[26:27]
	v_lshl_add_u64 v[26:27], s[26:27], 1, v[26:27]
	v_cvt_pk_bf16_f32 v33, v28, v29
	v_lshl_add_u64 v[26:27], v[26:27], 0, v[12:13]
	s_and_b64 vcc, exec, s[4:5]
	s_cbranch_vccnz .Lrope_ns_4
	v_mov_b64_e32 v[94:95], v[26:27]
	v_mov_b64_e32 v[96:97], v[30:31]
	v_mov_b64_e32 v[98:99], v[32:33]
	v_lshlrev_b32_e32 v26, 6, v152
	v_and_b32_e32 v26, 0x3f7c0, v26
	v_mov_b32_e32 v27, v13
	v_lshl_add_u64 v[34:35], v[140:141], 0, v[26:27]
	v_lshl_add_u64 v[26:27], v[142:143], 0, v[26:27]
	global_load_dwordx4 v[30:33], v[26:27], off offset:16
	global_load_dwordx4 v[42:45], v[26:27], off
	s_nop 0
	global_load_dwordx4 v[26:29], v[34:35], off offset:16
	global_load_dwordx4 v[38:41], v[34:35], off
	global_store_dwordx4 v[94:95], v[96:99], off offset:256
	v_and_b32_e32 v35, 64, v238
	v_xor_b32_e32 v34, 32, v238
	v_add_u32_e32 v35, 64, v35
	v_cmp_lt_i32_e32 vcc, v34, v35
	s_nop 1
	v_cndmask_b32_e32 v34, v238, v34, vcc
	v_lshlrev_b32_e32 v46, 2, v34
	ds_bpermute_b32 v34, v46, v22
	ds_bpermute_b32 v36, v46, v18
	ds_bpermute_b32 v35, v46, v23
	ds_bpermute_b32 v37, v46, v19
	ds_bpermute_b32 v52, v46, v24
	ds_bpermute_b32 v50, v46, v20
	ds_bpermute_b32 v53, v46, v25
	ds_bpermute_b32 v51, v46, v21
	s_waitcnt vmcnt(1) lgkmcnt(0)
	v_pk_mul_f32 v[30:31], v[30:31], v[36:37]
	v_pk_mul_f32 v[42:43], v[42:43], v[34:35]
	s_and_saveexec_b64 s[30:31], s[0:1]
	s_xor_b64 s[30:31], exec, s[30:31]
	v_pk_mul_f32 v[34:35], v[44:45], v[52:53]
	v_pk_mul_f32 v[32:33], v[32:33], v[50:51]
	v_pk_fma_f32 v[36:37], v[24:25], v[40:41], v[34:35]
	v_pk_fma_f32 v[34:35], v[22:23], v[38:39], v[42:43]
	v_pk_fma_f32 v[48:49], v[20:21], v[28:29], v[32:33]
	v_pk_fma_f32 v[46:47], v[18:19], v[26:27], v[30:31]
	s_andn2_saveexec_b64 s[30:31], s[30:31]
	v_pk_mul_f32 v[34:35], v[44:45], v[52:53]
	v_pk_fma_f32 v[46:47], v[18:19], v[26:27], v[30:31] neg_lo:[0,0,1] neg_hi:[0,0,1]
	v_pk_fma_f32 v[36:37], v[24:25], v[40:41], v[34:35] neg_lo:[0,0,1] neg_hi:[0,0,1]
	v_pk_fma_f32 v[34:35], v[22:23], v[38:39], v[42:43] neg_lo:[0,0,1] neg_hi:[0,0,1]
	v_pk_mul_f32 v[22:23], v[32:33], v[50:51]
	s_nop 0
	v_pk_fma_f32 v[48:49], v[20:21], v[28:29], v[22:23] neg_lo:[0,0,1] neg_hi:[0,0,1]
	s_or_b64 exec, exec, s[30:31]
	v_mov_b64_e32 v[18:19], v[46:47]
	v_mov_b64_e32 v[22:23], v[34:35]
	v_mov_b64_e32 v[20:21], v[48:49]
	v_mov_b64_e32 v[24:25], v[36:37]
	s_branch .LBB0_258
.Lrope_ns_4:
	global_store_dwordx4 v[26:27], v[30:33], off offset:256
	s_nop 1
; __device__ __forceinline__ unsigned pk2(float lo, float hi) { f32x2 v = {lo, hi}; bf16x2_t b = __builtin_convertvector(v, bf16x2_t); return __builtin_bit_cast(unsigned, b); }
;     __device__ __forceinline__ void operator()(const f32x4 (&acc)[2][2][4][2], const Unit& u, int wr, int wc, int fr, int fq) const {
;     ...
;                 for (int m = 0; m < 4; ++m) {
;                     const int row = u.pm * BM + ai * HALF + wr * 64 + m * 16 + fr;
;                     f32x4 v0 = acc[ai][bj][m][0], v1 = acc[ai][bj][m][1];
;                     if (rope) {
;                         const int s = row & (SEQ - 1), ib = 8 * (fq & 1);
;                         const f32x4 c0 = *(const f32x4*)(cosT + s * 16 + ib), c1 = *(const f32x4*)(cosT + s * 16 + ib + 4);
;                         const f32x4 s0 = *(const f32x4*)(sinT + s * 16 + ib), s1 = *(const f32x4*)(sinT + s * 16 + ib + 4);
;                         f32x4 p0, p1;
; #pragma unroll
;                         for (int e = 0; e < 4; ++e) { p0[e] = __shfl_xor(v0[e], 32); p1[e] = __shfl_xor(v1[e], 32); }
;                         if (fq < 2) { v0 = v0 * c0 - p0 * s0; v1 = v1 * c1 - p1 * s1; }
;                         else        { v0 = p0 * s0 + v0 * c0; v1 = p1 * s1 + v1 * c1; }
;                     }
;                     u32x4 w; w.x = pk2(v0[0], v0[1]); w.y = pk2(v0[2], v0[3]); w.z = pk2(v1[0], v1[1]); w.w = pk2(v1[2], v1[3]);
;                     *(u32x4*)(O + (size_t)row * ldc + cg0 + 8 * fq) = w;
.LBB0_258:
	v_cvt_pk_bf16_f32 v22, v22, v23
	v_cvt_pk_bf16_f32 v23, v24, v25
	v_cvt_pk_bf16_f32 v24, v18, v19
	v_mov_b64_e32 v[18:19], s[72:73]
	v_mad_i64_i32 v[18:19], s[30:31], v152, s19, v[18:19]
	v_lshl_add_u64 v[18:19], s[26:27], 1, v[18:19]
	v_cvt_pk_bf16_f32 v25, v20, v21
	v_lshl_add_u64 v[18:19], v[18:19], 0, v[12:13]
	s_and_b64 vcc, exec, s[4:5]
	s_cbranch_vccnz .Lrope_ns_5
	v_mov_b64_e32 v[94:95], v[18:19]
	v_mov_b64_e32 v[96:97], v[22:23]
	v_mov_b64_e32 v[98:99], v[24:25]
	v_lshlrev_b32_e32 v18, 6, v151
	v_and_b32_e32 v18, 0x3fbc0, v18
	v_mov_b32_e32 v19, v13
	v_lshl_add_u64 v[26:27], v[140:141], 0, v[18:19]
	v_lshl_add_u64 v[18:19], v[142:143], 0, v[18:19]
	global_load_dwordx4 v[22:25], v[18:19], off offset:16
	global_load_dwordx4 v[34:37], v[18:19], off
	s_nop 0
	global_load_dwordx4 v[18:21], v[26:27], off offset:16
	global_load_dwordx4 v[30:33], v[26:27], off
	global_store_dwordx4 v[94:95], v[96:99], off offset:256
	v_and_b32_e32 v27, 64, v238
	v_xor_b32_e32 v26, 32, v238
	v_add_u32_e32 v27, 64, v27
	v_cmp_lt_i32_e32 vcc, v26, v27
	s_nop 1
	v_cndmask_b32_e32 v26, v238, v26, vcc
	v_lshlrev_b32_e32 v38, 2, v26
	ds_bpermute_b32 v26, v38, v14
	ds_bpermute_b32 v28, v38, v8
	ds_bpermute_b32 v27, v38, v15
	ds_bpermute_b32 v29, v38, v9
	ds_bpermute_b32 v44, v38, v16
	ds_bpermute_b32 v42, v38, v10
	ds_bpermute_b32 v45, v38, v17
	ds_bpermute_b32 v43, v38, v11
	s_waitcnt vmcnt(1) lgkmcnt(0)
	v_pk_mul_f32 v[22:23], v[22:23], v[28:29]
	v_pk_mul_f32 v[34:35], v[34:35], v[26:27]
	s_and_saveexec_b64 s[30:31], s[0:1]
	s_xor_b64 s[30:31], exec, s[30:31]
	v_pk_mul_f32 v[26:27], v[36:37], v[44:45]
	v_pk_mul_f32 v[24:25], v[24:25], v[42:43]
	v_pk_fma_f32 v[28:29], v[16:17], v[32:33], v[26:27]
	v_pk_fma_f32 v[26:27], v[14:15], v[30:31], v[34:35]
	v_pk_fma_f32 v[40:41], v[10:11], v[20:21], v[24:25]
	v_pk_fma_f32 v[38:39], v[8:9], v[18:19], v[22:23]
	s_andn2_saveexec_b64 s[30:31], s[30:31]
	v_pk_mul_f32 v[26:27], v[36:37], v[44:45]
	v_pk_fma_f32 v[38:39], v[8:9], v[18:19], v[22:23] neg_lo:[0,0,1] neg_hi:[0,0,1]
	v_pk_fma_f32 v[28:29], v[16:17], v[32:33], v[26:27] neg_lo:[0,0,1] neg_hi:[0,0,1]
	v_pk_fma_f32 v[26:27], v[14:15], v[30:31], v[34:35] neg_lo:[0,0,1] neg_hi:[0,0,1]
	v_pk_mul_f32 v[14:15], v[24:25], v[42:43]
	s_nop 0
	v_pk_fma_f32 v[40:41], v[10:11], v[20:21], v[14:15] neg_lo:[0,0,1] neg_hi:[0,0,1]
	s_or_b64 exec, exec, s[30:31]
	v_mov_b64_e32 v[8:9], v[38:39]
	v_mov_b64_e32 v[14:15], v[26:27]
	v_mov_b64_e32 v[10:11], v[40:41]
	v_mov_b64_e32 v[16:17], v[28:29]
	s_branch .LBB0_264
.Lrope_ns_5:
	global_store_dwordx4 v[18:19], v[22:25], off offset:256
	s_nop 1
.LBB0_264:
	v_cvt_pk_bf16_f32 v14, v14, v15
	v_cvt_pk_bf16_f32 v15, v16, v17
	v_cvt_pk_bf16_f32 v16, v8, v9
	v_mov_b64_e32 v[8:9], s[72:73]
	v_mad_i64_i32 v[8:9], s[30:31], v151, s19, v[8:9]
	v_lshl_add_u64 v[8:9], s[26:27], 1, v[8:9]
	v_cvt_pk_bf16_f32 v17, v10, v11
	v_lshl_add_u64 v[8:9], v[8:9], 0, v[12:13]
	s_and_b64 vcc, exec, s[4:5]
	s_cbranch_vccnz .Lrope_ns_6
	v_mov_b64_e32 v[94:95], v[8:9]
	v_mov_b64_e32 v[96:97], v[14:15]
	v_mov_b64_e32 v[98:99], v[16:17]
	v_lshlrev_b32_e32 v8, 6, v150
	v_and_b32_e32 v8, 0x3ffc0, v8
	v_mov_b32_e32 v9, v13
	v_lshl_add_u64 v[18:19], v[140:141], 0, v[8:9]
	v_lshl_add_u64 v[8:9], v[142:143], 0, v[8:9]
	global_load_dwordx4 v[14:17], v[8:9], off offset:16
	global_load_dwordx4 v[26:29], v[8:9], off
	s_nop 0
	global_load_dwordx4 v[8:11], v[18:19], off offset:16
	global_load_dwordx4 v[22:25], v[18:19], off
	global_store_dwordx4 v[94:95], v[96:99], off offset:256
	v_and_b32_e32 v19, 64, v238
	v_xor_b32_e32 v18, 32, v238
	v_add_u32_e32 v19, 64, v19
	v_cmp_lt_i32_e32 vcc, v18, v19
	s_nop 1
	v_cndmask_b32_e32 v18, v238, v18, vcc
	v_lshlrev_b32_e32 v30, 2, v18
	ds_bpermute_b32 v18, v30, v4
	ds_bpermute_b32 v20, v30, v0
	ds_bpermute_b32 v19, v30, v5
	ds_bpermute_b32 v21, v30, v1
	ds_bpermute_b32 v36, v30, v6
	ds_bpermute_b32 v34, v30, v2
	ds_bpermute_b32 v37, v30, v7
	ds_bpermute_b32 v35, v30, v3
	s_waitcnt vmcnt(1) lgkmcnt(0)
	v_pk_mul_f32 v[14:15], v[14:15], v[20:21]
	v_pk_mul_f32 v[26:27], v[26:27], v[18:19]
	s_and_saveexec_b64 s[4:5], s[0:1]
	s_xor_b64 s[4:5], exec, s[4:5]
	v_pk_mul_f32 v[18:19], v[28:29], v[36:37]
	v_pk_mul_f32 v[16:17], v[16:17], v[34:35]
	v_pk_fma_f32 v[20:21], v[6:7], v[24:25], v[18:19]
	v_pk_fma_f32 v[18:19], v[4:5], v[22:23], v[26:27]
	v_pk_fma_f32 v[32:33], v[2:3], v[10:11], v[16:17]
	v_pk_fma_f32 v[30:31], v[0:1], v[8:9], v[14:15]
	s_andn2_saveexec_b64 s[4:5], s[4:5]
	v_pk_mul_f32 v[18:19], v[28:29], v[36:37]
	v_pk_fma_f32 v[30:31], v[0:1], v[8:9], v[14:15] neg_lo:[0,0,1] neg_hi:[0,0,1]
	v_pk_fma_f32 v[20:21], v[6:7], v[24:25], v[18:19] neg_lo:[0,0,1] neg_hi:[0,0,1]
	v_pk_fma_f32 v[18:19], v[4:5], v[22:23], v[26:27] neg_lo:[0,0,1] neg_hi:[0,0,1]
	v_pk_mul_f32 v[4:5], v[16:17], v[34:35]
	s_nop 0
	v_pk_fma_f32 v[32:33], v[2:3], v[10:11], v[4:5] neg_lo:[0,0,1] neg_hi:[0,0,1]
	s_or_b64 exec, exec, s[4:5]
	v_mov_b64_e32 v[0:1], v[30:31]
	v_mov_b64_e32 v[4:5], v[18:19]
	v_mov_b64_e32 v[2:3], v[32:33]
	v_mov_b64_e32 v[6:7], v[20:21]
	s_branch .LBB0_270
.Lrope_ns_6:
	global_store_dwordx4 v[8:9], v[14:17], off offset:256
	s_nop 1
